# v61 + rec_et HL/CA stores widened dwordx2->dwordx4 via v_permlane32_swap (asm guide 7.3)
# speedup vs baseline: 1.0124x; 1.0036x over previous
; __device__ __forceinline__ unsigned cvtpk(float lo, float hi) { f32x2_t v = {lo, hi}; bf16x2_t b = __builtin_convertvector(v, bf16x2_t); return __builtin_bit_cast(unsigned, b); }
; __device__ __forceinline__ void rec_et(LAS unsigned char* lds, const RecArgs& a, const bf16_t* Wr, const bf16_t* Wi, const int et, const int n, const int r32, const int hi, ...
;     ...
;                 if (valid) {
; #pragma unroll
;                     for (int g4 = 0; g4 < 4; ++g4) { const int ch0 = 64 * n + 32 * et + 8 * g4 + 4 * hi; const size_t off = (size_t)(b * TT + t) * 512 + ch0;
;                         *(u32x2*)(a.HL + off) = (u32x2){cvtpk(uv[4 * g4], uv[4 * g4 + 1]), cvtpk(uv[4 * g4 + 2], uv[4 * g4 + 3])};
;                         *(u32x2*)(a.CA + off) = (u32x2){cvtpk(av[4 * g4], av[4 * g4 + 1]), cvtpk(av[4 * g4 + 2], av[4 * g4 + 3])}; }
;                 }
.LBB0_476:
	s_and_saveexec_b64 s[10:11], s[38:39]
	s_cbranch_execz .LBB0_478
	v_add_u32_e32 v82, s20, v250
	v_mbcnt_lo_u32_b32 v88, -1, 0
	v_mbcnt_hi_u32_b32 v88, -1, v88
	v_lshlrev_b32_e32 v82, 9, v82
	v_and_b32_e32 v88, 32, v88
	v_lshrrev_b32_e32 v88, 3, v88
	v_or_b32_e32 v82, v82, v88
	v_add_lshl_u32 v83, v82, v94, 1
	v_add_lshl_u32 v89, v82, v98, 1
	v_cvt_pk_bf16_f32 v84, v26, v27
	v_cvt_pk_bf16_f32 v85, v28, v29
	v_cvt_pk_bf16_f32 v86, v18, v19
	v_cvt_pk_bf16_f32 v87, v20, v21
	s_nop 1
	v_permlane32_swap_b32_e32 v84, v86
	v_permlane32_swap_b32_e32 v85, v87
	global_store_dwordx4 v83, v[84:87], s[12:13]
	s_nop 1
	v_cvt_pk_bf16_f32 v84, v30, v31
	v_cvt_pk_bf16_f32 v85, v32, v33
	v_cvt_pk_bf16_f32 v86, v22, v23
	v_cvt_pk_bf16_f32 v87, v24, v25
	s_nop 1
	v_permlane32_swap_b32_e32 v84, v86
	v_permlane32_swap_b32_e32 v85, v87
	global_store_dwordx4 v83, v[84:87], s[22:23]
	s_nop 1
	v_cvt_pk_bf16_f32 v84, v10, v11
	v_cvt_pk_bf16_f32 v85, v12, v13
	v_cvt_pk_bf16_f32 v86, v2, v3
	v_cvt_pk_bf16_f32 v87, v208, v209
	s_nop 1
	v_permlane32_swap_b32_e32 v84, v86
	v_permlane32_swap_b32_e32 v85, v87
	global_store_dwordx4 v89, v[84:87], s[12:13]
	s_nop 1
	v_cvt_pk_bf16_f32 v84, v14, v15
	v_cvt_pk_bf16_f32 v85, v16, v17
	v_cvt_pk_bf16_f32 v86, v6, v7
	v_cvt_pk_bf16_f32 v87, v206, v207
	s_nop 1
	v_permlane32_swap_b32_e32 v84, v86
	v_permlane32_swap_b32_e32 v85, v87
	global_store_dwordx4 v89, v[84:87], s[22:23]
	s_nop 1

; __device__ __forceinline__ unsigned cvtpk(float lo, float hi) { f32x2_t v = {lo, hi}; bf16x2_t b = __builtin_convertvector(v, bf16x2_t); return __builtin_bit_cast(unsigned, b); }
; __device__ __forceinline__ void rec_et(LAS unsigned char* lds, const RecArgs& a, const bf16_t* Wr, const bf16_t* Wi, const int et, const int n, const int r32, const int hi, ...
;     ...
;                 if (valid) {
; #pragma unroll
;                     for (int g4 = 0; g4 < 4; ++g4) { const int ch0 = 64 * n + 32 * et + 8 * g4 + 4 * hi; const size_t off = (size_t)(b * TT + t) * 512 + ch0;
;                         *(u32x2*)(a.HL + off) = (u32x2){cvtpk(uv[4 * g4], uv[4 * g4 + 1]), cvtpk(uv[4 * g4 + 2], uv[4 * g4 + 3])};
;                         *(u32x2*)(a.CA + off) = (u32x2){cvtpk(av[4 * g4], av[4 * g4 + 1]), cvtpk(av[4 * g4 + 2], av[4 * g4 + 3])}; }
;                 }
.LBB0_486:
	s_and_saveexec_b64 s[8:9], s[38:39]
	s_cbranch_execz .LBB0_488
	v_add_u32_e32 v82, s20, v250
	v_mbcnt_lo_u32_b32 v88, -1, 0
	v_mbcnt_hi_u32_b32 v88, -1, v88
	v_lshlrev_b32_e32 v82, 9, v82
	v_and_b32_e32 v88, 32, v88
	v_lshrrev_b32_e32 v88, 3, v88
	v_or_b32_e32 v82, v82, v88
	v_add_lshl_u32 v83, v82, v106, 1
	v_add_lshl_u32 v89, v82, v110, 1
	v_cvt_pk_bf16_f32 v84, v26, v27
	v_cvt_pk_bf16_f32 v85, v28, v29
	v_cvt_pk_bf16_f32 v86, v18, v19
	v_cvt_pk_bf16_f32 v87, v20, v21
	s_nop 1
	v_permlane32_swap_b32_e32 v84, v86
	v_permlane32_swap_b32_e32 v85, v87
	global_store_dwordx4 v83, v[84:87], s[12:13]
	s_nop 1
	v_cvt_pk_bf16_f32 v84, v30, v31
	v_cvt_pk_bf16_f32 v85, v32, v33
	v_cvt_pk_bf16_f32 v86, v22, v23
	v_cvt_pk_bf16_f32 v87, v24, v25
	s_nop 1
	v_permlane32_swap_b32_e32 v84, v86
	v_permlane32_swap_b32_e32 v85, v87
	global_store_dwordx4 v83, v[84:87], s[22:23]
	s_nop 1
	v_cvt_pk_bf16_f32 v84, v10, v11
	v_cvt_pk_bf16_f32 v85, v12, v13
	v_cvt_pk_bf16_f32 v86, v2, v3
	v_cvt_pk_bf16_f32 v87, v208, v209
	s_nop 1
	v_permlane32_swap_b32_e32 v84, v86
	v_permlane32_swap_b32_e32 v85, v87
	global_store_dwordx4 v89, v[84:87], s[12:13]
	s_nop 1
	v_cvt_pk_bf16_f32 v84, v14, v15
	v_cvt_pk_bf16_f32 v85, v16, v17
	v_cvt_pk_bf16_f32 v86, v6, v7
	v_cvt_pk_bf16_f32 v87, v206, v207
	s_nop 1
	v_permlane32_swap_b32_e32 v84, v86
	v_permlane32_swap_b32_e32 v85, v87
	global_store_dwordx4 v89, v[84:87], s[22:23]
	s_nop 1
